# v8 + prologue layer-0 pre-norm loop: input pointers hoisted out of the loop (no per-row kernarg load) and next-row L2 touch with counted vmcnt(4) wait
# baseline (speedup 1.0000x reference)
; __device__ __forceinline__ int lbid() { int b = (int)blockIdx.x; asm volatile("" : "+s"(b)); return b; }
; __device__ __forceinline__ const float* xin_rows(const AV& a, int tok0) { return tok0 < NTOK_P ? AIN(I_XP) + (size_t)tok0 * DM : AIN(I_XS) + (size_t)(tok0 - NTOK_P) * DM; }
; __device__ __forceinline__ void step_pro_a(const AV& a, LAS unsigned char* lds) {
;     ...
;     { const float* g = AIN(I_NORMG); bf16* HN0 = (bf16*)(ws + WS_HN0); f32x4 gv[4];
; #pragma unroll
;       for (int j = 0; j < 4; ++j) gv[j] = *((const f32x4*)g + lane + 64 * j);
;       for (int m = lbid() * NWAVES + wave; m < NTOK; m += G * NWAVES) {
;           const f32x4* xr = (const f32x4*)(xin_rows(a, m)) + lane; f32x4 v[4]; float ssum = 0.f;
; #pragma unroll
;           for (int j = 0; j < 4; ++j) { v[j] = xr[64 * j]; ssum += (v[j].x * v[j].x + v[j].y * v[j].y) + (v[j].z * v[j].z + v[j].w * v[j].w); }
;           const float rs = 1.0f / sqrtf(wave_sum(ssum) * (1.0f / DM) + EPS);
.LBB0_421:
	s_or_b64 exec, exec, s[2:3]
	s_load_dwordx2 s[2:3], s[0:1], 0x18
	v_and_b32_e32 v26, 63, v24
	v_mov_b32_e32 v19, v1
	v_lshlrev_b32_e32 v18, 4, v26
	v_ashrrev_i32_e32 v25, 6, v24
	s_waitcnt lgkmcnt(0)
	v_lshl_add_u64 v[14:15], s[2:3], 0, v[18:19]
	flat_load_dwordx4 v[2:5], v[14:15]
	flat_load_dwordx4 v[6:9], v[14:15] offset:1024
	flat_load_dwordx4 v[10:13], v[14:15] offset:2048
	s_nop 0
	flat_load_dwordx4 v[14:17], v[14:15] offset:3072
	s_mov_b32 s2, s68
	s_nop 0
	v_lshl_add_u32 v20, s2, 3, v25
	s_mov_b32 s2, 0x18000
	v_cmp_gt_i32_e32 vcc, s2, v20
	s_and_saveexec_b64 s[2:3], vcc
	s_cbranch_execz .LBB0_424
	s_load_dwordx2 s[6:7], s[0:1], 0xe8
	v_ashrrev_i32_e32 v21, 31, v20
	v_mov_b32_e32 v104, 0
	global_load_dwordx4 v[104:107], v104, s[0:1]
	s_waitcnt vmcnt(0) lgkmcnt(0)
	v_mov_b32_e32 v22, v3
	v_mov_b32_e32 v23, v5
	v_mov_b32_e32 v3, v4
	v_mov_b32_e32 v4, v7
	v_mov_b32_e32 v5, v9
	v_mov_b32_e32 v7, v8
	v_mov_b32_e32 v8, v11
	v_mov_b32_e32 v9, v13
	v_mov_b32_e32 v11, v12
	v_mov_b32_e32 v12, v15
	v_mov_b32_e32 v13, v17
	v_mov_b32_e32 v15, v16
	v_lshlrev_b64 v[16:17], 11, v[20:21]
	s_lshl_b32 s4, s60, 3
	v_lshl_or_b32 v16, v26, 3, v16
	v_lshl_add_u64 v[16:17], s[6:7], 0, v[16:17]
	s_mov_b64 s[6:7], 0x2a800000
	s_ashr_i32 s5, s4, 31
	v_lshl_add_u64 v[16:17], v[16:17], 0, s[6:7]
	s_lshl_b64 s[6:7], s[4:5], 11
	s_lshl_b64 s[98:99], s[4:5], 12
	s_mov_b64 s[42:43], 0
.LBB0_423:
	v_add_u32_e32 v0, 0xffff0000, v20
	v_cmp_gt_i32_e32 vcc, s73, v20
	v_mov_b32_e32 v19, v1
	v_mov_b32_e32 v27, v210
	v_cndmask_b32_e32 v28, v0, v20, vcc
	v_cndmask_b32_e32 v30, v106, v104, vcc
	v_cndmask_b32_e32 v31, v107, v105, vcc
	v_cndmask_b32_e32 v29, 0, v21, vcc
	v_lshlrev_b64 v[28:29], 12, v[28:29]
	v_mov_b32_e32 v44, v210
	v_mov_b32_e32 v45, v210
	v_mov_b32_e32 v46, v210
	v_mov_b32_e32 v47, v210
	v_mov_b32_e32 v48, v210
	v_lshl_add_u64 v[20:21], v[20:21], 0, s[4:5]
	v_cmp_lt_i32_e32 vcc, s67, v20
	s_or_b64 s[42:43], vcc, s[42:43]
	v_lshl_add_u64 v[28:29], v[30:31], 0, v[28:29]
	v_lshl_add_u64 v[40:41], v[28:29], 0, v[18:19]
	v_subrev_u32_e32 v0, s4, v20
	v_cmp_le_i32_e32 vcc, s73, v20
	v_cmp_gt_i32_e64 s[40:41], s73, v0
	v_mov_b32_e32 v101, s98
	v_mov_b32_e32 v103, s99
	s_and_b64 s[40:41], vcc, s[40:41]
	v_cmp_ge_i32_e32 vcc, s67, v20
	s_nop 1
	s_andn2_b64 vcc, vcc, s[40:41]
	s_nop 1
	v_cndmask_b32_e32 v102, 0, v101, vcc
	v_cndmask_b32_e32 v103, 0, v103, vcc
	s_nop 0
	v_lshl_add_u64 v[102:103], v[40:41], 0, v[102:103]
	flat_load_dwordx4 v[28:31], v[40:41]
	flat_load_dwordx4 v[32:35], v[40:41] offset:1024
	flat_load_dwordx4 v[36:39], v[40:41] offset:2048
	s_nop 0
	flat_load_dwordx4 v[40:43], v[40:41] offset:3072
	global_load_dword v100, v[102:103], off
	global_load_dword v100, v[102:103], off offset:1024
	global_load_dword v100, v[102:103], off offset:2048
	global_load_dword v100, v[102:103], off offset:3072
	s_nop 0
	v_lshlrev_b32_e32 v0, 2, v27
	v_lshlrev_b32_e32 v19, 2, v44
	v_lshlrev_b32_e32 v27, 2, v45
	v_lshlrev_b32_e32 v44, 2, v46
	v_lshlrev_b32_e32 v45, 2, v47
	v_lshlrev_b32_e32 v46, 2, v48
	v_bitop3_b32 v59, v44, 32, v216 bitop3:0x6c
	v_bitop3_b32 v60, v45, 64, v216 bitop3:0x6c
	v_bitop3_b32 v61, v46, s33, v216 bitop3:0x6c
	v_bitop3_b32 v58, v0, 4, v216 bitop3:0x6c
	v_bitop3_b32 v19, v19, 8, v216 bitop3:0x6c
	v_bitop3_b32 v27, v27, 16, v216 bitop3:0x6c
	s_waitcnt vmcnt(4) lgkmcnt(0)
	v_pk_mul_f32 v[44:45], v[30:31], v[30:31]
	v_pk_mul_f32 v[46:47], v[28:29], v[28:29]
	v_pk_mul_f32 v[48:49], v[34:35], v[34:35]
	v_pk_mul_f32 v[50:51], v[32:33], v[32:33]
	v_mul_f32_e32 v0, v37, v37
	v_mul_f32_e32 v62, v42, v42
	v_mul_f32_e32 v52, v39, v39
	v_mul_f32_e32 v64, v40, v40
	v_mul_f32_e32 v65, v41, v41
	v_mov_b32_e32 v56, v40
	v_mov_b32_e32 v57, v42
	v_mov_b32_e32 v42, v41
	v_pk_mov_b32 v[40:41], v[46:47], v[44:45] op_sel:[1,0]
	v_mov_b32_e32 v47, v45
	v_pk_mov_b32 v[44:45], v[50:51], v[48:49] op_sel:[1,0]
	v_mov_b32_e32 v51, v49
	v_mov_b32_e32 v54, v28
	v_mov_b32_e32 v55, v30
	v_mov_b32_e32 v30, v29
	v_mov_b32_e32 v28, v32
	v_mov_b32_e32 v29, v34
	v_mov_b32_e32 v34, v33
	v_mov_b32_e32 v32, v36
	v_mov_b32_e32 v33, v38
	v_pk_fma_f32 v[48:49], v[36:37], v[36:37], v[0:1] op_sel_hi:[1,1,0]
	v_pk_fma_f32 v[52:53], v[38:39], v[38:39], v[52:53] op_sel_hi:[1,1,0]
	v_mov_b32_e32 v38, v37
	v_pk_add_f32 v[36:37], v[40:41], v[46:47]
	v_pk_add_f32 v[40:41], v[44:45], v[50:51]
	v_mul_f32_e32 v63, v43, v43
	v_pk_add_f32 v[36:37], v[36:37], v[36:37] op_sel:[0,1] op_sel_hi:[1,0]
	v_pk_add_f32 v[40:41], v[40:41], v[40:41] op_sel:[0,1] op_sel_hi:[1,0]
	v_mov_b32_e32 v49, v62
	v_mov_b32_e32 v53, v63
	v_mov_b32_e32 v37, v64
	v_mov_b32_e32 v41, v65
	v_pk_add_f32 v[44:45], v[48:49], v[52:53]
	v_pk_add_f32 v[36:37], v[36:37], v[40:41]
	s_nop 0
	v_pk_add_f32 v[36:37], v[36:37], v[44:45]
	s_nop 0
	v_add_f32_e32 v0, v36, v37
	ds_bpermute_b32 v36, v58, v0
	s_waitcnt lgkmcnt(0)
	v_add_f32_e32 v0, v0, v36
	ds_bpermute_b32 v19, v19, v0
	s_waitcnt lgkmcnt(0)
	v_add_f32_e32 v0, v0, v19
	ds_bpermute_b32 v19, v27, v0
	s_waitcnt lgkmcnt(0)
	v_add_f32_e32 v0, v0, v19
	ds_bpermute_b32 v19, v59, v0
	s_waitcnt lgkmcnt(0)
	v_add_f32_e32 v0, v0, v19
	ds_bpermute_b32 v19, v60, v0
	s_waitcnt lgkmcnt(0)
	v_add_f32_e32 v0, v0, v19
	ds_bpermute_b32 v19, v61, v0
	s_waitcnt lgkmcnt(0)
; __device__ __forceinline__ unsigned pk2(float lo, float hi) { return f2bf(lo) | (f2bf(hi) << 16); }
; __device__ __forceinline__ void step_pro_a(const AV& a, LAS unsigned char* lds) {
;     ...
;           const float rs = 1.0f / sqrtf(wave_sum(ssum) * (1.0f / DM) + EPS);
;           u32x2* o8 = (u32x2*)(HN0 + (size_t)m * DM) + lane;
; #pragma unroll
;           for (int j = 0; j < 4; ++j) { u32x2 w; w.x = pk2(v[j].x * rs * gv[j].x, v[j].y * rs * gv[j].y); w.y = pk2(v[j].z * rs * gv[j].z, v[j].w * rs * gv[j].w); o8[64 * j] = w; } } }
	v_add_f32_e32 v0, v0, v19
	v_fmamk_f32 v0, v0, 0x3a800000, v211
	v_mul_f32_e32 v19, 0x4f800000, v0
	v_cmp_gt_f32_e32 vcc, s69, v0
	s_nop 1
	v_cndmask_b32_e32 v0, v0, v19, vcc
	v_sqrt_f32_e32 v19, v0
	s_nop 0
	v_add_u32_e32 v27, -1, v19
	v_add_u32_e32 v36, 1, v19
	v_fma_f32 v37, -v27, v19, v0
	v_fma_f32 v40, -v36, v19, v0
	v_cmp_ge_f32_e64 s[40:41], 0, v37
	s_nop 1
	v_cndmask_b32_e64 v19, v19, v27, s[40:41]
	v_cmp_lt_f32_e64 s[40:41], 0, v40
	s_nop 1
	v_cndmask_b32_e64 v19, v19, v36, s[40:41]
	v_mul_f32_e32 v27, 0x37800000, v19
	v_cndmask_b32_e32 v19, v19, v27, vcc
	v_cmp_class_f32_e32 vcc, v0, v212
	s_nop 1
	v_cndmask_b32_e32 v0, v19, v0, vcc
	v_div_scale_f32 v19, s[12:13], v0, v0, 1.0
	v_rcp_f32_e32 v36, v19
	v_div_scale_f32 v27, vcc, 1.0, v0, 1.0
	v_fma_f32 v37, -v19, v36, 1.0
	v_fmac_f32_e32 v36, v37, v36
	v_mul_f32_e32 v37, v27, v36
	v_fma_f32 v40, -v19, v37, v27
	v_fmac_f32_e32 v37, v40, v36
	v_fma_f32 v19, -v19, v37, v27
	v_div_fmas_f32 v19, v19, v36, v37
	v_div_fixup_f32 v0, v19, v0, 1.0
	v_pk_mul_f32 v[30:31], v[30:31], v[0:1] op_sel_hi:[1,0]
	v_pk_mul_f32 v[34:35], v[34:35], v[0:1] op_sel_hi:[1,0]
	v_pk_mul_f32 v[36:37], v[38:39], v[0:1] op_sel_hi:[1,0]
	v_pk_mul_f32 v[38:39], v[42:43], v[0:1] op_sel_hi:[1,0]
	v_pk_mul_f32 v[40:41], v[54:55], v[0:1] op_sel_hi:[1,0]
	v_pk_mul_f32 v[28:29], v[28:29], v[0:1] op_sel_hi:[1,0]
	v_pk_mul_f32 v[30:31], v[22:23], v[30:31]
	v_pk_mul_f32 v[32:33], v[32:33], v[0:1] op_sel_hi:[1,0]
	v_pk_mul_f32 v[42:43], v[56:57], v[0:1] op_sel_hi:[1,0]
	v_pk_mul_f32 v[40:41], v[2:3], v[40:41]
	v_pk_mul_f32 v[28:29], v[6:7], v[28:29]
	v_pk_mul_f32 v[34:35], v[4:5], v[34:35]
	v_pk_mul_f32 v[36:37], v[8:9], v[36:37]
	v_pk_mul_f32 v[38:39], v[12:13], v[38:39]
	v_and_b32_sdwa v27, v31, v213 dst_sel:DWORD dst_unused:UNUSED_PAD src0_sel:WORD_1 src1_sel:DWORD
	v_and_b32_sdwa v44, v30, v213 dst_sel:DWORD dst_unused:UNUSED_PAD src0_sel:WORD_1 src1_sel:DWORD
	v_pk_mul_f32 v[32:33], v[10:11], v[32:33]
	v_pk_mul_f32 v[42:43], v[14:15], v[42:43]
	v_and_b32_sdwa v0, v40, v213 dst_sel:DWORD dst_unused:UNUSED_PAD src0_sel:WORD_1 src1_sel:DWORD
	v_and_b32_sdwa v19, v41, v213 dst_sel:DWORD dst_unused:UNUSED_PAD src0_sel:WORD_1 src1_sel:DWORD
	v_and_b32_sdwa v45, v28, v213 dst_sel:DWORD dst_unused:UNUSED_PAD src0_sel:WORD_1 src1_sel:DWORD
	v_and_b32_sdwa v46, v29, v213 dst_sel:DWORD dst_unused:UNUSED_PAD src0_sel:WORD_1 src1_sel:DWORD
	v_and_b32_sdwa v47, v35, v213 dst_sel:DWORD dst_unused:UNUSED_PAD src0_sel:WORD_1 src1_sel:DWORD
	v_and_b32_sdwa v48, v34, v213 dst_sel:DWORD dst_unused:UNUSED_PAD src0_sel:WORD_1 src1_sel:DWORD
	v_and_b32_sdwa v51, v37, v213 dst_sel:DWORD dst_unused:UNUSED_PAD src0_sel:WORD_1 src1_sel:DWORD
	v_and_b32_sdwa v52, v36, v213 dst_sel:DWORD dst_unused:UNUSED_PAD src0_sel:WORD_1 src1_sel:DWORD
	v_and_b32_sdwa v55, v39, v213 dst_sel:DWORD dst_unused:UNUSED_PAD src0_sel:WORD_1 src1_sel:DWORD
	v_and_b32_sdwa v56, v38, v213 dst_sel:DWORD dst_unused:UNUSED_PAD src0_sel:WORD_1 src1_sel:DWORD
	v_add3_u32 v27, v31, v27, s50
	v_add3_u32 v30, v30, v44, s50
	v_and_b32_sdwa v49, v32, v213 dst_sel:DWORD dst_unused:UNUSED_PAD src0_sel:WORD_1 src1_sel:DWORD
	v_and_b32_sdwa v50, v33, v213 dst_sel:DWORD dst_unused:UNUSED_PAD src0_sel:WORD_1 src1_sel:DWORD
	v_and_b32_sdwa v53, v42, v213 dst_sel:DWORD dst_unused:UNUSED_PAD src0_sel:WORD_1 src1_sel:DWORD
	v_and_b32_sdwa v54, v43, v213 dst_sel:DWORD dst_unused:UNUSED_PAD src0_sel:WORD_1 src1_sel:DWORD
	v_add3_u32 v0, v40, v0, s50
	v_add3_u32 v19, v41, v19, s50
	v_add3_u32 v40, v28, v45, s50
	v_add3_u32 v31, v29, v46, s50
	v_add3_u32 v28, v35, v47, s50
	v_add3_u32 v29, v34, v48, s50
	v_add3_u32 v34, v37, v51, s50
	v_add3_u32 v35, v36, v52, s50
	v_add3_u32 v39, v39, v55, s50
	v_add3_u32 v38, v38, v56, s50
	v_and_b32_e32 v27, 0xffff0000, v27
	v_and_b32_e32 v30, 0xffff0000, v30
	v_add3_u32 v32, v32, v49, s50
	v_add3_u32 v33, v33, v50, s50
	v_add3_u32 v36, v42, v53, s50
	v_add3_u32 v37, v43, v54, s50
	v_and_b32_e32 v41, 0xffff0000, v28
	v_and_b32_e32 v42, 0xffff0000, v29
	v_and_b32_e32 v34, 0xffff0000, v34
	v_and_b32_e32 v35, 0xffff0000, v35
	v_and_b32_e32 v39, 0xffff0000, v39
	v_and_b32_e32 v38, 0xffff0000, v38
	v_or_b32_sdwa v29, v27, v19 dst_sel:DWORD dst_unused:UNUSED_PAD src0_sel:DWORD src1_sel:WORD_1
	v_or_b32_sdwa v28, v30, v0 dst_sel:DWORD dst_unused:UNUSED_PAD src0_sel:DWORD src1_sel:WORD_1
	v_or_b32_sdwa v31, v41, v31 dst_sel:DWORD dst_unused:UNUSED_PAD src0_sel:DWORD src1_sel:WORD_1
	v_or_b32_sdwa v30, v42, v40 dst_sel:DWORD dst_unused:UNUSED_PAD src0_sel:DWORD src1_sel:WORD_1
	v_or_b32_sdwa v33, v34, v33 dst_sel:DWORD dst_unused:UNUSED_PAD src0_sel:DWORD src1_sel:WORD_1
	v_or_b32_sdwa v32, v35, v32 dst_sel:DWORD dst_unused:UNUSED_PAD src0_sel:DWORD src1_sel:WORD_1
	v_or_b32_sdwa v35, v39, v37 dst_sel:DWORD dst_unused:UNUSED_PAD src0_sel:DWORD src1_sel:WORD_1
	v_or_b32_sdwa v34, v38, v36 dst_sel:DWORD dst_unused:UNUSED_PAD src0_sel:DWORD src1_sel:WORD_1
	flat_store_dwordx2 v[16:17], v[28:29]
	flat_store_dwordx2 v[16:17], v[30:31] offset:512
	flat_store_dwordx2 v[16:17], v[32:33] offset:1024
	flat_store_dwordx2 v[16:17], v[34:35] offset:1536
	v_lshl_add_u64 v[16:17], v[16:17], 0, s[6:7]
	s_andn2_b64 exec, exec, s[42:43]
	s_cbranch_execnz .LBB0_423
